# MoBA packed loop: staging wait ladder (vmcnt 7..0) collapsed to one vmcnt(0) before the LDS writes
# baseline (speedup 1.0000x reference)
.LBB0_1924:
	s_add_i32 s22, s26, 0x20000
	s_sub_i32 s22, s22, s56
	v_add_u32_e32 v2, s22, v188
	s_waitcnt vmcnt(0)
	ds_write_b128 v243, v[128:131]
	ds_write_b128 v244, v[132:135] offset:4608
	ds_write_b128 v243, v[136:139] offset:1152
	ds_write_b128 v244, v[140:143] offset:5120
	ds_write_b128 v243, v[144:147] offset:2304
	ds_write_b128 v244, v[148:151] offset:5632
	ds_write_b128 v243, v[152:155] offset:3456
	ds_write_b128 v244, v[156:159] offset:6144
	v_add_u32_e32 v4, 0x4000, v2
	global_load_dwordx4 v[128:131], v2, s[40:41]
	global_load_dwordx4 v[132:135], v2, s[42:43]
	v_add_u32_e32 v5, 0x8000, v2
	global_load_dwordx4 v[136:139], v4, s[40:41]
	global_load_dwordx4 v[140:143], v4, s[42:43]
	v_add_u32_e32 v6, 0xc000, v2
	global_load_dwordx4 v[144:147], v5, s[40:41]
	global_load_dwordx4 v[148:151], v5, s[42:43]
	v_xor_b32_e32 v112, 0x80000000, v1
	global_load_dwordx4 v[152:155], v6, s[40:41]
	global_load_dwordx4 v[156:159], v6, s[42:43]
	s_waitcnt lgkmcnt(0)
	ds_read_b128 v[6:9], v242
	ds_read_b128 v[2:5], v242 offset:32
	ds_read_b128 v[10:13], v242 offset:8704
	v_mov_b32_e32 v113, v112
	v_mov_b32_e32 v114, v112
	v_mov_b32_e32 v115, v112
	v_mov_b32_e32 v116, v112
	v_mov_b32_e32 v117, v112
	v_mov_b32_e32 v118, v112
	v_mov_b32_e32 v119, v112
	v_mov_b32_e32 v120, v112
	v_mov_b32_e32 v121, v112
	v_mov_b32_e32 v122, v112
	v_mov_b32_e32 v123, v112
	v_mov_b32_e32 v124, v112
	v_mov_b32_e32 v125, v112
	v_mov_b32_e32 v126, v112
	v_mov_b32_e32 v127, v112
	ds_read_b128 v[96:99], v242 offset:8736
	s_andn2_b64 vcc, exec, s[20:21]
	s_waitcnt lgkmcnt(1)
	v_mfma_f32_32x32x16_bf16 v[112:127], v[6:9], v[10:13], v[112:127]
	s_waitcnt lgkmcnt(0)
	v_mfma_f32_32x32x16_bf16 v[112:127], v[2:5], v[96:99], v[112:127]
	ds_read_b128 v[10:13], v242 offset:64
	ds_read_b128 v[96:99], v242 offset:8768
	ds_read_b128 v[160:163], v242 offset:96
	ds_read_b128 v[100:103], v242 offset:8800
	s_waitcnt lgkmcnt(2)
	v_mfma_f32_32x32x16_bf16 v[112:127], v[10:13], v[96:99], v[112:127]
	v_xor_b32_e32 v96, 0x80000000, v15
	v_cndmask_b32_e64 v97, 0, 1, s[20:21]
	v_cmp_ne_u32_e64 s[22:23], 1, v97
	v_mov_b32_e32 v97, v96
	v_mov_b32_e32 v98, v96
	v_mov_b32_e32 v99, v96
	v_mov_b32_e32 v104, v96
	s_waitcnt lgkmcnt(0)
	v_mfma_f32_32x32x16_bf16 v[112:127], v[160:163], v[100:103], v[112:127]
	v_mov_b32_e32 v100, v96
	v_mov_b32_e32 v101, v96
	v_mov_b32_e32 v102, v96
	v_mov_b32_e32 v103, v96
	v_mov_b32_e32 v105, v96
	v_mov_b32_e32 v106, v96
	v_mov_b32_e32 v107, v96
	v_mov_b32_e32 v108, v96
	s_cbranch_vccnz .Lmb_one
	ds_read_b128 v[246:249], v242 offset:13312
	ds_read_b128 v[250:253], v242 offset:13344
	v_mov_b32_e32 v109, v96
	v_mov_b32_e32 v110, v96
	v_mov_b32_e32 v111, v96
	s_waitcnt lgkmcnt(1)
	s_nop 0
	v_mfma_f32_32x32x16_bf16 v[96:111], v[6:9], v[246:249], v[96:111]
	s_waitcnt lgkmcnt(0)
	v_mfma_f32_32x32x16_bf16 v[96:111], v[2:5], v[250:253], v[96:111]
	ds_read_b128 v[2:5], v242 offset:13376
	ds_read_b128 v[6:9], v242 offset:13408
	s_waitcnt lgkmcnt(1)
	v_mfma_f32_32x32x16_bf16 v[96:111], v[10:13], v[2:5], v[96:111]
	s_waitcnt lgkmcnt(0)
	v_mfma_f32_32x32x16_bf16 v[96:111], v[160:163], v[6:9], v[96:111]
